# per-step dispatch: both kernarg pointer loads issued together (one scalar-load latency per step instead of two)
# speedup vs baseline: 1.0140x; 1.0031x over previous
.LBB0_223:
	v_readlane_b32 s88, v249, 0
	v_mov_b32_e32 v138, v174
	v_readlane_b32 s89, v249, 1
	s_load_dwordx2 s[20:21], s[88:89], 0x98
	s_load_dwordx2 s[52:53], s[88:89], 0x90
	s_cmp_lg_u32 s80, 14
	v_add_u32_e32 v186, s76, v138
	s_cbranch_scc1 .LBB0_238
	v_cmp_eq_u32_e32 vcc, 0, v186
	s_and_saveexec_b64 s[0:1], vcc
	s_cbranch_execz .LBB0_237
	s_waitcnt lgkmcnt(0)
	global_load_dword v0, v175, s[20:21] sc1
	s_add_u32 s2, s20, 0x5e24000
	s_addc_u32 s3, s21, 0
	s_waitcnt vmcnt(0)
	v_cmp_le_u32_e32 vcc, s86, v0
	s_cbranch_vccnz .LBB0_236
	s_mov_b32 s8, 0x3ffff8
	s_branch .LBB0_228

.LBB0_238:
	s_waitcnt lgkmcnt(0)
	s_cmp_gt_u32 s80, 13
	s_cselect_b64 s[8:9], -1, 0
	s_waitcnt lgkmcnt(0)
	s_add_u32 s62, s20, 0x8000000
	s_addc_u32 s63, s21, 0
	s_add_u32 s0, s52, s72
	s_addc_u32 s1, s53, 0
	v_readlane_b32 s2, v247, 9
	v_readlane_b32 s3, v247, 10
	s_add_u32 s28, s0, s2
	s_addc_u32 s29, s1, s3
	s_add_u32 s0, s20, 0x5e40000
	v_writelane_b32 v247, s0, 41
	s_addc_u32 s0, s21, 0
	v_writelane_b32 v247, s0, 42
	s_add_u32 s0, s20, s82
	s_addc_u32 s1, s21, 0
	s_add_u32 s0, s0, s2
	s_addc_u32 s1, s1, s3
	s_add_u32 s2, s0, 0xc000000
	s_addc_u32 s3, s1, 0
	s_add_u32 s0, s2, s66
	v_writelane_b32 v247, s2, 43
	s_addc_u32 s1, s3, 0
	s_mov_b64 s[38:39], -1
	v_writelane_b32 v247, s3, 44
	s_mov_b64 s[44:45], 0
	v_readlane_b32 s2, v247, 0
	s_add_u32 s2, s20, s2
	s_addc_u32 s3, s21, 0
	v_readlane_b32 s4, v247, 2
	s_add_u32 s2, s2, s4
	v_readlane_b32 s4, v247, 1
	s_addc_u32 s3, s3, s4
	s_add_u32 s2, s2, 0x10000000
	s_addc_u32 s3, s3, 0
	v_writelane_b32 v247, s2, 45
	s_add_u32 s4, s2, s66
	v_writelane_b32 v247, s3, 46
	s_addc_u32 s5, s3, 0
	v_readlane_b32 s2, v247, 3
	s_add_u32 s2, s4, s2
	s_mov_b64 s[78:79], 0
	v_writelane_b32 v247, s2, 47
	s_addc_u32 s2, s5, 0
	v_writelane_b32 v247, s2, 48
	v_writelane_b32 v247, s8, 49
	s_and_b64 s[2:3], s[8:9], exec
	s_cselect_b32 s2, 0x2b00000, 0
	s_add_u32 s64, s20, s2
	v_writelane_b32 v247, s9, 50
	s_addc_u32 s65, s21, 0
	v_sub_co_u32_e64 v0, s[8:9], s80, 14
	s_and_b64 s[8:9], s[8:9], exec
	v_readfirstlane_b32 s8, v0
	s_cselect_b32 s81, s80, s8
	s_mov_b32 s3, s91
	s_cmp_lt_i32 s81, 6
	s_mov_b64 s[58:59], 0
	s_mov_b64 s[36:37], 0
	s_mov_b64 s[54:55], 0
	s_cbranch_scc1 .LBB0_257
	s_cmp_gt_i32 s81, 8
	s_cbranch_scc0 .LBB0_249
	s_mov_b64 s[36:37], -1
	s_cmp_gt_i32 s81, 10
	s_cbranch_scc0 .LBB0_246
	s_cmp_gt_i32 s81, 12
	s_cbranch_scc0 .LBB0_243
	s_cmp_eq_u32 s81, 13
	s_mov_b64 s[36:37], 0
	s_mov_b64 s[58:59], -1
	s_cselect_b64 s[54:55], -1, 0
